# P1: the last unit's epilogue of each workgroup uses write-through (sc1) stores so the L2 write-back overlaps the epilogue instead of following it at the grid barrier
# speedup vs baseline: 1.0071x; 1.0034x over previous
; __device__ __forceinline__ u32x2 pack4(f32x4 v) { u32x2 w; w.x = cvt_pk_bf16(v[0], v[1]); w.y = cvt_pk_bf16(v[2], v[3]); return w; }
; template <int EK>
; __device__ __forceinline__ void epi_tile(const f32x4 (&acc)[2][2][4][2], const Unit& u, int wr, int wc, int fr, int fq, const EpiArgs& E, const LAS float* rt) {
;     ...
;             if (EK == EK_SCALE) {
;                 const float r = rr[ai][m];
; #pragma unroll
;                 for (int bj = 0; bj < 2; ++bj) { const int col = u.pn * BM + bj * HALF + wc * 32 + fq * 8;
;                     const u32x2 lo = pack4(acc[ai][bj][m][0] * r), hi = pack4(acc[ai][bj][m][1] * r);
;                     *(u32x4*)(E.ob + (size_t)row * E.ldb + col) = (u32x4){lo.x, lo.y, hi.x, hi.y}; }
.LBB0_201:
	s_cmp_lg_u64 s[4:5], 0
	s_cbranch_scc1 .Lmy_wt_p1
	v_lshl_add_u32 v146, s56, 10, v153
	ds_read2_b32 v[160:161], v146 offset1:16
	ds_read2_b32 v[162:163], v146 offset0:32 offset1:48
	ds_read2_b32 v[150:151], v146 offset0:128 offset1:144
	ds_read2_b32 v[146:147], v146 offset0:160 offset1:176
	v_lshl_add_u32 v164, s66, 8, v1
	s_waitcnt lgkmcnt(0)
	v_pk_mul_f32 v[158:159], v[112:113], v[160:161] op_sel_hi:[1,0]
	v_pk_mul_f32 v[156:157], v[110:111], v[160:161] op_sel_hi:[1,0]
	v_lshl_or_b32 v148, s68, 8, v154
	v_ashrrev_i32_e32 v165, 31, v164
	v_cvt_pk_bf16_f32 v156, v156, v157
	v_cvt_pk_bf16_f32 v157, v158, v159
	v_pk_mul_f32 v[166:167], v[108:109], v[160:161] op_sel_hi:[1,0]
	v_pk_mul_f32 v[158:159], v[106:107], v[160:161] op_sel_hi:[1,0]
	v_ashrrev_i32_e32 v149, 31, v148
	v_cvt_pk_bf16_f32 v158, v158, v159
	v_cvt_pk_bf16_f32 v159, v166, v167
	v_lshlrev_b64 v[166:167], 12, v[164:165]
	v_lshl_add_u64 v[166:167], s[64:65], 0, v[166:167]
	v_lshlrev_b64 v[168:169], 1, v[148:149]
	v_lshl_add_u64 v[148:149], v[166:167], 0, v[168:169]
	global_store_dwordx4 v[148:149], v[156:159], off
	v_pk_mul_f32 v[166:167], v[76:77], v[160:161] op_sel_hi:[1,0]
	s_add_u32 s78, s58, 0xffffff00
	v_pk_mul_f32 v[158:159], v[80:81], v[160:161] op_sel_hi:[1,0]
	v_pk_mul_f32 v[156:157], v[78:79], v[160:161] op_sel_hi:[1,0]
	s_addc_u32 s79, s59, -1
	v_cvt_pk_bf16_f32 v156, v156, v157
	v_cvt_pk_bf16_f32 v157, v158, v159
	v_pk_mul_f32 v[158:159], v[74:75], v[160:161] op_sel_hi:[1,0]
	v_mov_b32_e32 v160, v161
	v_cvt_pk_bf16_f32 v158, v158, v159
	v_cvt_pk_bf16_f32 v159, v166, v167
	v_or_b32_e32 v166, 16, v164
	v_ashrrev_i32_e32 v167, 31, v166
	global_store_dwordx4 v[148:149], v[156:159], off offset:256
	v_lshlrev_b64 v[166:167], 12, v[166:167]
	v_lshl_add_u64 v[166:167], s[64:65], 0, v[166:167]
	v_pk_mul_f32 v[158:159], v[104:105], v[160:161] op_sel_hi:[1,0]
	v_pk_mul_f32 v[156:157], v[102:103], v[160:161] op_sel_hi:[1,0]
	v_pk_mul_f32 v[170:171], v[100:101], v[160:161] op_sel_hi:[1,0]
	v_cvt_pk_bf16_f32 v156, v156, v157
	v_cvt_pk_bf16_f32 v157, v158, v159
	v_pk_mul_f32 v[158:159], v[98:99], v[160:161] op_sel_hi:[1,0]
	v_lshl_add_u64 v[166:167], v[166:167], 0, v[168:169]
	v_cvt_pk_bf16_f32 v158, v158, v159
	v_cvt_pk_bf16_f32 v159, v170, v171
	global_store_dwordx4 v[166:167], v[156:159], off
	v_pk_mul_f32 v[170:171], v[68:69], v[160:161] op_sel_hi:[1,0]
	s_mov_b64 s[58:59], 0x80000
	v_pk_mul_f32 v[158:159], v[72:73], v[160:161] op_sel_hi:[1,0]
	v_pk_mul_f32 v[156:157], v[70:71], v[160:161] op_sel_hi:[1,0]
	s_nop 0
	v_cvt_pk_bf16_f32 v156, v156, v157
	v_cvt_pk_bf16_f32 v157, v158, v159
	v_pk_mul_f32 v[158:159], v[66:67], v[160:161] op_sel_hi:[1,0]
	v_or_b32_e32 v160, 32, v164
	v_cvt_pk_bf16_f32 v158, v158, v159
	v_cvt_pk_bf16_f32 v159, v170, v171
	v_ashrrev_i32_e32 v161, 31, v160
	global_store_dwordx4 v[166:167], v[156:159], off offset:256
	v_lshlrev_b64 v[160:161], 12, v[160:161]
	v_lshl_add_u64 v[160:161], s[64:65], 0, v[160:161]
	v_pk_mul_f32 v[158:159], v[96:97], v[162:163] op_sel_hi:[1,0]
	v_pk_mul_f32 v[156:157], v[94:95], v[162:163] op_sel_hi:[1,0]
	v_pk_mul_f32 v[166:167], v[92:93], v[162:163] op_sel_hi:[1,0]
	v_cvt_pk_bf16_f32 v156, v156, v157
	v_cvt_pk_bf16_f32 v157, v158, v159
	v_pk_mul_f32 v[158:159], v[90:91], v[162:163] op_sel_hi:[1,0]
	v_lshl_add_u64 v[160:161], v[160:161], 0, v[168:169]
	v_cvt_pk_bf16_f32 v158, v158, v159
	v_cvt_pk_bf16_f32 v159, v166, v167
	global_store_dwordx4 v[160:161], v[156:159], off
	v_pk_mul_f32 v[166:167], v[60:61], v[162:163] op_sel_hi:[1,0]
	s_nop 0
	v_pk_mul_f32 v[158:159], v[64:65], v[162:163] op_sel_hi:[1,0]
	v_pk_mul_f32 v[156:157], v[62:63], v[162:163] op_sel_hi:[1,0]
	s_nop 0
	v_cvt_pk_bf16_f32 v156, v156, v157
	v_cvt_pk_bf16_f32 v157, v158, v159
	v_pk_mul_f32 v[158:159], v[58:59], v[162:163] op_sel_hi:[1,0]
	v_mov_b32_e32 v162, v163
	v_cvt_pk_bf16_f32 v158, v158, v159
	v_cvt_pk_bf16_f32 v159, v166, v167
	global_store_dwordx4 v[160:161], v[156:159], off offset:256
	v_or_b32_e32 v160, 48, v164
	v_ashrrev_i32_e32 v161, 31, v160
	v_pk_mul_f32 v[158:159], v[88:89], v[162:163] op_sel_hi:[1,0]
	v_pk_mul_f32 v[156:157], v[86:87], v[162:163] op_sel_hi:[1,0]
	v_lshlrev_b64 v[160:161], 12, v[160:161]
	v_cvt_pk_bf16_f32 v156, v156, v157
	v_cvt_pk_bf16_f32 v157, v158, v159
	v_pk_mul_f32 v[158:159], v[82:83], v[162:163] op_sel_hi:[1,0]
	v_lshl_add_u64 v[160:161], s[64:65], 0, v[160:161]
	v_pk_mul_f32 v[164:165], v[84:85], v[162:163] op_sel_hi:[1,0]
	v_cvt_pk_bf16_f32 v158, v158, v159
	v_lshl_add_u64 v[160:161], v[160:161], 0, v[168:169]
	v_cvt_pk_bf16_f32 v159, v164, v165
	global_store_dwordx4 v[160:161], v[156:159], off
	v_pk_mul_f32 v[164:165], v[52:53], v[162:163] op_sel_hi:[1,0]
	s_nop 0
	v_pk_mul_f32 v[158:159], v[56:57], v[162:163] op_sel_hi:[1,0]
	v_pk_mul_f32 v[156:157], v[54:55], v[162:163] op_sel_hi:[1,0]
	s_nop 0
	v_cvt_pk_bf16_f32 v156, v156, v157
	v_cvt_pk_bf16_f32 v157, v158, v159
	v_pk_mul_f32 v[158:159], v[50:51], v[162:163] op_sel_hi:[1,0]
	s_nop 0
	v_cvt_pk_bf16_f32 v158, v158, v159
	v_cvt_pk_bf16_f32 v159, v164, v165
	global_store_dwordx4 v[160:161], v[156:159], off offset:256
	v_pk_mul_f32 v[160:161], v[44:45], v[150:151] op_sel_hi:[1,0]
	s_nop 0
	v_pk_mul_f32 v[158:159], v[48:49], v[150:151] op_sel_hi:[1,0]
	v_pk_mul_f32 v[156:157], v[46:47], v[150:151] op_sel_hi:[1,0]
	s_nop 0
	v_cvt_pk_bf16_f32 v156, v156, v157
	v_cvt_pk_bf16_f32 v157, v158, v159
	v_pk_mul_f32 v[158:159], v[42:43], v[150:151] op_sel_hi:[1,0]
	s_nop 0
	v_cvt_pk_bf16_f32 v158, v158, v159
	v_cvt_pk_bf16_f32 v159, v160, v161
	v_lshl_add_u64 v[160:161], v[148:149], 0, s[58:59]
	s_mov_b32 s58, 0x80000
	v_add_co_u32_e32 v162, vcc, s58, v148
; __device__ __forceinline__ u32x2 pack4(f32x4 v) { u32x2 w; w.x = cvt_pk_bf16(v[0], v[1]); w.y = cvt_pk_bf16(v[2], v[3]); return w; }
; template <int EK>
; __device__ __forceinline__ void epi_tile(const f32x4 (&acc)[2][2][4][2], const Unit& u, int wr, int wc, int fr, int fq, const EpiArgs& E, const LAS float* rt) {
;     ...
;             if (EK == EK_SCALE) {
;                 const float r = rr[ai][m];
; #pragma unroll
;                 for (int bj = 0; bj < 2; ++bj) { const int col = u.pn * BM + bj * HALF + wc * 32 + fq * 8;
;                     const u32x2 lo = pack4(acc[ai][bj][m][0] * r), hi = pack4(acc[ai][bj][m][1] * r);
;                     *(u32x4*)(E.ob + (size_t)row * E.ldb + col) = (u32x4){lo.x, lo.y, hi.x, hi.y}; }
	s_mov_b64 s[58:59], 0x90000
	s_nop 0
	v_addc_co_u32_e32 v163, vcc, 0, v149, vcc
	global_store_dwordx4 v[162:163], v[156:159], off
	v_pk_mul_f32 v[162:163], v[12:13], v[150:151] op_sel_hi:[1,0]
	s_nop 0
	v_pk_mul_f32 v[158:159], v[16:17], v[150:151] op_sel_hi:[1,0]
	v_pk_mul_f32 v[156:157], v[14:15], v[150:151] op_sel_hi:[1,0]
	s_nop 0
	v_cvt_pk_bf16_f32 v156, v156, v157
	v_cvt_pk_bf16_f32 v157, v158, v159
	v_pk_mul_f32 v[158:159], v[10:11], v[150:151] op_sel_hi:[1,0]
	v_mov_b32_e32 v150, v151
	v_cvt_pk_bf16_f32 v158, v158, v159
	v_cvt_pk_bf16_f32 v159, v162, v163
	global_store_dwordx4 v[160:161], v[156:159], off offset:256
	v_pk_mul_f32 v[160:161], v[36:37], v[150:151] op_sel_hi:[1,0]
	s_nop 0
	v_pk_mul_f32 v[158:159], v[40:41], v[150:151] op_sel_hi:[1,0]
	v_pk_mul_f32 v[156:157], v[38:39], v[150:151] op_sel_hi:[1,0]
	s_nop 0
	v_cvt_pk_bf16_f32 v156, v156, v157
	v_cvt_pk_bf16_f32 v157, v158, v159
	v_pk_mul_f32 v[158:159], v[34:35], v[150:151] op_sel_hi:[1,0]
	s_nop 0
	v_cvt_pk_bf16_f32 v158, v158, v159
	v_cvt_pk_bf16_f32 v159, v160, v161
	v_lshl_add_u64 v[160:161], v[148:149], 0, s[58:59]
	s_mov_b32 s58, 0x90000
	v_add_co_u32_e32 v162, vcc, s58, v148
	s_mov_b64 s[58:59], 0xa0000
	s_nop 0
	v_addc_co_u32_e32 v163, vcc, 0, v149, vcc
	global_store_dwordx4 v[162:163], v[156:159], off
	v_pk_mul_f32 v[162:163], v[4:5], v[150:151] op_sel_hi:[1,0]
	s_nop 0
	v_pk_mul_f32 v[156:157], v[6:7], v[150:151] op_sel_hi:[1,0]
	v_pk_mul_f32 v[158:159], v[8:9], v[150:151] op_sel_hi:[1,0]
	v_cvt_pk_bf16_f32 v156, v156, v157
	v_pk_mul_f32 v[150:151], v[2:3], v[150:151] op_sel_hi:[1,0]
	v_cvt_pk_bf16_f32 v157, v158, v159
	v_cvt_pk_bf16_f32 v159, v162, v163
	s_nop 0
	v_cvt_pk_bf16_f32 v158, v150, v151
	global_store_dwordx4 v[160:161], v[156:159], off offset:256
	v_pk_mul_f32 v[150:151], v[32:33], v[146:147] op_sel_hi:[1,0]
	s_nop 0
	v_pk_mul_f32 v[156:157], v[30:31], v[146:147] op_sel_hi:[1,0]
	v_pk_mul_f32 v[158:159], v[26:27], v[146:147] op_sel_hi:[1,0]
	v_cvt_pk_bf16_f32 v156, v156, v157
	v_cvt_pk_bf16_f32 v157, v150, v151
	v_pk_mul_f32 v[150:151], v[28:29], v[146:147] op_sel_hi:[1,0]
	v_cvt_pk_bf16_f32 v158, v158, v159
	s_nop 0
	v_cvt_pk_bf16_f32 v159, v150, v151
	v_lshl_add_u64 v[150:151], v[148:149], 0, s[58:59]
	s_mov_b32 s58, 0xa0000
	v_add_co_u32_e32 v160, vcc, s58, v148
	s_mov_b64 s[58:59], 0xb0000
	s_nop 0
	v_addc_co_u32_e32 v161, vcc, 0, v149, vcc
	global_store_dwordx4 v[160:161], v[156:159], off
	v_pk_mul_f32 v[160:161], v[120:121], v[146:147] op_sel_hi:[1,0]
	s_nop 0
	v_pk_mul_f32 v[158:159], v[116:117], v[146:147] op_sel_hi:[1,0]
	v_pk_mul_f32 v[156:157], v[114:115], v[146:147] op_sel_hi:[1,0]
	s_nop 0
	v_cvt_pk_bf16_f32 v156, v156, v157
	v_cvt_pk_bf16_f32 v157, v158, v159
	v_pk_mul_f32 v[158:159], v[118:119], v[146:147] op_sel_hi:[1,0]
	s_nop 0
	v_cvt_pk_bf16_f32 v158, v158, v159
	v_cvt_pk_bf16_f32 v159, v160, v161
	global_store_dwordx4 v[150:151], v[156:159], off offset:256
	v_mov_b32_e32 v150, v147
	v_pk_mul_f32 v[146:147], v[24:25], v[150:151] op_sel_hi:[1,0]
	v_pk_mul_f32 v[156:157], v[22:23], v[150:151] op_sel_hi:[1,0]
	v_pk_mul_f32 v[158:159], v[18:19], v[150:151] op_sel_hi:[1,0]
	v_cvt_pk_bf16_f32 v156, v156, v157
	v_cvt_pk_bf16_f32 v157, v146, v147
	v_pk_mul_f32 v[146:147], v[20:21], v[150:151] op_sel_hi:[1,0]
	v_lshl_add_u64 v[160:161], v[148:149], 0, s[58:59]
	s_mov_b32 s58, 0xb0000
	v_cvt_pk_bf16_f32 v158, v158, v159
	v_cvt_pk_bf16_f32 v159, v146, v147
	v_add_co_u32_e32 v146, vcc, s58, v148
	s_nop 1
	v_addc_co_u32_e32 v147, vcc, 0, v149, vcc
	global_store_dwordx4 v[146:147], v[156:159], off
	v_pk_mul_f32 v[148:149], v[124:125], v[150:151] op_sel_hi:[1,0]
	v_pk_mul_f32 v[146:147], v[122:123], v[150:151] op_sel_hi:[1,0]
	v_pk_mul_f32 v[156:157], v[128:129], v[150:151] op_sel_hi:[1,0]
	v_cvt_pk_bf16_f32 v146, v146, v147
	v_cvt_pk_bf16_f32 v147, v148, v149
	v_pk_mul_f32 v[148:149], v[126:127], v[150:151] op_sel_hi:[1,0]
	s_andn2_b64 vcc, exec, s[6:7]
	v_cvt_pk_bf16_f32 v148, v148, v149
	v_cvt_pk_bf16_f32 v149, v156, v157
	global_store_dwordx4 v[160:161], v[146:149], off offset:256
	s_branch .Lmy_wtj_p1
.Lmy_wt_p1:
	v_lshl_add_u32 v146, s56, 10, v153
	ds_read2_b32 v[160:161], v146 offset1:16
	ds_read2_b32 v[162:163], v146 offset0:32 offset1:48
	ds_read2_b32 v[150:151], v146 offset0:128 offset1:144
	ds_read2_b32 v[146:147], v146 offset0:160 offset1:176
	v_lshl_add_u32 v164, s66, 8, v1
	s_waitcnt lgkmcnt(0)
; __device__ __forceinline__ u32x2 pack4(f32x4 v) { u32x2 w; w.x = cvt_pk_bf16(v[0], v[1]); w.y = cvt_pk_bf16(v[2], v[3]); return w; }
; template <int EK>
; __device__ __forceinline__ void epi_tile(const f32x4 (&acc)[2][2][4][2], const Unit& u, int wr, int wc, int fr, int fq, const EpiArgs& E, const LAS float* rt) {
;     ...
;             if (EK == EK_SCALE) {
;                 const float r = rr[ai][m];
; #pragma unroll
;                 for (int bj = 0; bj < 2; ++bj) { const int col = u.pn * BM + bj * HALF + wc * 32 + fq * 8;
;                     const u32x2 lo = pack4(acc[ai][bj][m][0] * r), hi = pack4(acc[ai][bj][m][1] * r);
;                     *(u32x4*)(E.ob + (size_t)row * E.ldb + col) = (u32x4){lo.x, lo.y, hi.x, hi.y}; }
	v_pk_mul_f32 v[158:159], v[112:113], v[160:161] op_sel_hi:[1,0]
	v_pk_mul_f32 v[156:157], v[110:111], v[160:161] op_sel_hi:[1,0]
	v_lshl_or_b32 v148, s68, 8, v154
	v_ashrrev_i32_e32 v165, 31, v164
	v_cvt_pk_bf16_f32 v156, v156, v157
	v_cvt_pk_bf16_f32 v157, v158, v159
	v_pk_mul_f32 v[166:167], v[108:109], v[160:161] op_sel_hi:[1,0]
	v_pk_mul_f32 v[158:159], v[106:107], v[160:161] op_sel_hi:[1,0]
	v_ashrrev_i32_e32 v149, 31, v148
	v_cvt_pk_bf16_f32 v158, v158, v159
	v_cvt_pk_bf16_f32 v159, v166, v167
	v_lshlrev_b64 v[166:167], 12, v[164:165]
	v_lshl_add_u64 v[166:167], s[64:65], 0, v[166:167]
	v_lshlrev_b64 v[168:169], 1, v[148:149]
	v_lshl_add_u64 v[148:149], v[166:167], 0, v[168:169]
	global_store_dwordx4 v[148:149], v[156:159], off sc1
	v_pk_mul_f32 v[166:167], v[76:77], v[160:161] op_sel_hi:[1,0]
	s_add_u32 s78, s58, 0xffffff00
	v_pk_mul_f32 v[158:159], v[80:81], v[160:161] op_sel_hi:[1,0]
	v_pk_mul_f32 v[156:157], v[78:79], v[160:161] op_sel_hi:[1,0]
	s_addc_u32 s79, s59, -1
	v_cvt_pk_bf16_f32 v156, v156, v157
	v_cvt_pk_bf16_f32 v157, v158, v159
	v_pk_mul_f32 v[158:159], v[74:75], v[160:161] op_sel_hi:[1,0]
	v_mov_b32_e32 v160, v161
	v_cvt_pk_bf16_f32 v158, v158, v159
	v_cvt_pk_bf16_f32 v159, v166, v167
	v_or_b32_e32 v166, 16, v164
	v_ashrrev_i32_e32 v167, 31, v166
	global_store_dwordx4 v[148:149], v[156:159], off offset:256 sc1
	v_lshlrev_b64 v[166:167], 12, v[166:167]
	v_lshl_add_u64 v[166:167], s[64:65], 0, v[166:167]
	v_pk_mul_f32 v[158:159], v[104:105], v[160:161] op_sel_hi:[1,0]
	v_pk_mul_f32 v[156:157], v[102:103], v[160:161] op_sel_hi:[1,0]
	v_pk_mul_f32 v[170:171], v[100:101], v[160:161] op_sel_hi:[1,0]
	v_cvt_pk_bf16_f32 v156, v156, v157
	v_cvt_pk_bf16_f32 v157, v158, v159
	v_pk_mul_f32 v[158:159], v[98:99], v[160:161] op_sel_hi:[1,0]
	v_lshl_add_u64 v[166:167], v[166:167], 0, v[168:169]
	v_cvt_pk_bf16_f32 v158, v158, v159
	v_cvt_pk_bf16_f32 v159, v170, v171
	global_store_dwordx4 v[166:167], v[156:159], off sc1
	v_pk_mul_f32 v[170:171], v[68:69], v[160:161] op_sel_hi:[1,0]
	s_mov_b64 s[58:59], 0x80000
	v_pk_mul_f32 v[158:159], v[72:73], v[160:161] op_sel_hi:[1,0]
	v_pk_mul_f32 v[156:157], v[70:71], v[160:161] op_sel_hi:[1,0]
	s_nop 0
	v_cvt_pk_bf16_f32 v156, v156, v157
	v_cvt_pk_bf16_f32 v157, v158, v159
	v_pk_mul_f32 v[158:159], v[66:67], v[160:161] op_sel_hi:[1,0]
	v_or_b32_e32 v160, 32, v164
	v_cvt_pk_bf16_f32 v158, v158, v159
	v_cvt_pk_bf16_f32 v159, v170, v171
	v_ashrrev_i32_e32 v161, 31, v160
	global_store_dwordx4 v[166:167], v[156:159], off offset:256 sc1
	v_lshlrev_b64 v[160:161], 12, v[160:161]
	v_lshl_add_u64 v[160:161], s[64:65], 0, v[160:161]
	v_pk_mul_f32 v[158:159], v[96:97], v[162:163] op_sel_hi:[1,0]
	v_pk_mul_f32 v[156:157], v[94:95], v[162:163] op_sel_hi:[1,0]
	v_pk_mul_f32 v[166:167], v[92:93], v[162:163] op_sel_hi:[1,0]
	v_cvt_pk_bf16_f32 v156, v156, v157
	v_cvt_pk_bf16_f32 v157, v158, v159
	v_pk_mul_f32 v[158:159], v[90:91], v[162:163] op_sel_hi:[1,0]
	v_lshl_add_u64 v[160:161], v[160:161], 0, v[168:169]
	v_cvt_pk_bf16_f32 v158, v158, v159
	v_cvt_pk_bf16_f32 v159, v166, v167
	global_store_dwordx4 v[160:161], v[156:159], off sc1
	v_pk_mul_f32 v[166:167], v[60:61], v[162:163] op_sel_hi:[1,0]
	s_nop 0
	v_pk_mul_f32 v[158:159], v[64:65], v[162:163] op_sel_hi:[1,0]
	v_pk_mul_f32 v[156:157], v[62:63], v[162:163] op_sel_hi:[1,0]
	s_nop 0
	v_cvt_pk_bf16_f32 v156, v156, v157
	v_cvt_pk_bf16_f32 v157, v158, v159
	v_pk_mul_f32 v[158:159], v[58:59], v[162:163] op_sel_hi:[1,0]
	v_mov_b32_e32 v162, v163
	v_cvt_pk_bf16_f32 v158, v158, v159
	v_cvt_pk_bf16_f32 v159, v166, v167
	global_store_dwordx4 v[160:161], v[156:159], off offset:256 sc1
	v_or_b32_e32 v160, 48, v164
	v_ashrrev_i32_e32 v161, 31, v160
	v_pk_mul_f32 v[158:159], v[88:89], v[162:163] op_sel_hi:[1,0]
	v_pk_mul_f32 v[156:157], v[86:87], v[162:163] op_sel_hi:[1,0]
	v_lshlrev_b64 v[160:161], 12, v[160:161]
	v_cvt_pk_bf16_f32 v156, v156, v157
	v_cvt_pk_bf16_f32 v157, v158, v159
	v_pk_mul_f32 v[158:159], v[82:83], v[162:163] op_sel_hi:[1,0]
	v_lshl_add_u64 v[160:161], s[64:65], 0, v[160:161]
	v_pk_mul_f32 v[164:165], v[84:85], v[162:163] op_sel_hi:[1,0]
	v_cvt_pk_bf16_f32 v158, v158, v159
	v_lshl_add_u64 v[160:161], v[160:161], 0, v[168:169]
	v_cvt_pk_bf16_f32 v159, v164, v165
	global_store_dwordx4 v[160:161], v[156:159], off sc1
	v_pk_mul_f32 v[164:165], v[52:53], v[162:163] op_sel_hi:[1,0]
	s_nop 0
	v_pk_mul_f32 v[158:159], v[56:57], v[162:163] op_sel_hi:[1,0]
	v_pk_mul_f32 v[156:157], v[54:55], v[162:163] op_sel_hi:[1,0]
	s_nop 0
	v_cvt_pk_bf16_f32 v156, v156, v157
	v_cvt_pk_bf16_f32 v157, v158, v159
	v_pk_mul_f32 v[158:159], v[50:51], v[162:163] op_sel_hi:[1,0]
	s_nop 0
	v_cvt_pk_bf16_f32 v158, v158, v159
	v_cvt_pk_bf16_f32 v159, v164, v165
	global_store_dwordx4 v[160:161], v[156:159], off offset:256 sc1
; __device__ __forceinline__ u32x2 pack4(f32x4 v) { u32x2 w; w.x = cvt_pk_bf16(v[0], v[1]); w.y = cvt_pk_bf16(v[2], v[3]); return w; }
; template <int EK>
; __device__ __forceinline__ void epi_tile(const f32x4 (&acc)[2][2][4][2], const Unit& u, int wr, int wc, int fr, int fq, const EpiArgs& E, const LAS float* rt) {
;     ...
;             if (EK == EK_SCALE) {
;                 const float r = rr[ai][m];
; #pragma unroll
;                 for (int bj = 0; bj < 2; ++bj) { const int col = u.pn * BM + bj * HALF + wc * 32 + fq * 8;
;                     const u32x2 lo = pack4(acc[ai][bj][m][0] * r), hi = pack4(acc[ai][bj][m][1] * r);
;                     *(u32x4*)(E.ob + (size_t)row * E.ldb + col) = (u32x4){lo.x, lo.y, hi.x, hi.y}; }
	v_pk_mul_f32 v[160:161], v[44:45], v[150:151] op_sel_hi:[1,0]
	s_nop 0
	v_pk_mul_f32 v[158:159], v[48:49], v[150:151] op_sel_hi:[1,0]
	v_pk_mul_f32 v[156:157], v[46:47], v[150:151] op_sel_hi:[1,0]
	s_nop 0
	v_cvt_pk_bf16_f32 v156, v156, v157
	v_cvt_pk_bf16_f32 v157, v158, v159
	v_pk_mul_f32 v[158:159], v[42:43], v[150:151] op_sel_hi:[1,0]
	s_nop 0
	v_cvt_pk_bf16_f32 v158, v158, v159
	v_cvt_pk_bf16_f32 v159, v160, v161
	v_lshl_add_u64 v[160:161], v[148:149], 0, s[58:59]
	s_mov_b32 s58, 0x80000
	v_add_co_u32_e32 v162, vcc, s58, v148
	s_mov_b64 s[58:59], 0x90000
	s_nop 0
	v_addc_co_u32_e32 v163, vcc, 0, v149, vcc
	global_store_dwordx4 v[162:163], v[156:159], off sc1
	v_pk_mul_f32 v[162:163], v[12:13], v[150:151] op_sel_hi:[1,0]
	s_nop 0
	v_pk_mul_f32 v[158:159], v[16:17], v[150:151] op_sel_hi:[1,0]
	v_pk_mul_f32 v[156:157], v[14:15], v[150:151] op_sel_hi:[1,0]
	s_nop 0
	v_cvt_pk_bf16_f32 v156, v156, v157
	v_cvt_pk_bf16_f32 v157, v158, v159
	v_pk_mul_f32 v[158:159], v[10:11], v[150:151] op_sel_hi:[1,0]
	v_mov_b32_e32 v150, v151
	v_cvt_pk_bf16_f32 v158, v158, v159
	v_cvt_pk_bf16_f32 v159, v162, v163
	global_store_dwordx4 v[160:161], v[156:159], off offset:256 sc1
	v_pk_mul_f32 v[160:161], v[36:37], v[150:151] op_sel_hi:[1,0]
	s_nop 0
	v_pk_mul_f32 v[158:159], v[40:41], v[150:151] op_sel_hi:[1,0]
	v_pk_mul_f32 v[156:157], v[38:39], v[150:151] op_sel_hi:[1,0]
	s_nop 0
	v_cvt_pk_bf16_f32 v156, v156, v157
	v_cvt_pk_bf16_f32 v157, v158, v159
	v_pk_mul_f32 v[158:159], v[34:35], v[150:151] op_sel_hi:[1,0]
	s_nop 0
	v_cvt_pk_bf16_f32 v158, v158, v159
	v_cvt_pk_bf16_f32 v159, v160, v161
	v_lshl_add_u64 v[160:161], v[148:149], 0, s[58:59]
	s_mov_b32 s58, 0x90000
	v_add_co_u32_e32 v162, vcc, s58, v148
	s_mov_b64 s[58:59], 0xa0000
	s_nop 0
	v_addc_co_u32_e32 v163, vcc, 0, v149, vcc
	global_store_dwordx4 v[162:163], v[156:159], off sc1
	v_pk_mul_f32 v[162:163], v[4:5], v[150:151] op_sel_hi:[1,0]
	s_nop 0
	v_pk_mul_f32 v[156:157], v[6:7], v[150:151] op_sel_hi:[1,0]
	v_pk_mul_f32 v[158:159], v[8:9], v[150:151] op_sel_hi:[1,0]
	v_cvt_pk_bf16_f32 v156, v156, v157
	v_pk_mul_f32 v[150:151], v[2:3], v[150:151] op_sel_hi:[1,0]
	v_cvt_pk_bf16_f32 v157, v158, v159
	v_cvt_pk_bf16_f32 v159, v162, v163
	s_nop 0
	v_cvt_pk_bf16_f32 v158, v150, v151
	global_store_dwordx4 v[160:161], v[156:159], off offset:256 sc1
	v_pk_mul_f32 v[150:151], v[32:33], v[146:147] op_sel_hi:[1,0]
	s_nop 0
	v_pk_mul_f32 v[156:157], v[30:31], v[146:147] op_sel_hi:[1,0]
	v_pk_mul_f32 v[158:159], v[26:27], v[146:147] op_sel_hi:[1,0]
	v_cvt_pk_bf16_f32 v156, v156, v157
	v_cvt_pk_bf16_f32 v157, v150, v151
	v_pk_mul_f32 v[150:151], v[28:29], v[146:147] op_sel_hi:[1,0]
	v_cvt_pk_bf16_f32 v158, v158, v159
	s_nop 0
	v_cvt_pk_bf16_f32 v159, v150, v151
	v_lshl_add_u64 v[150:151], v[148:149], 0, s[58:59]
	s_mov_b32 s58, 0xa0000
	v_add_co_u32_e32 v160, vcc, s58, v148
	s_mov_b64 s[58:59], 0xb0000
	s_nop 0
	v_addc_co_u32_e32 v161, vcc, 0, v149, vcc
	global_store_dwordx4 v[160:161], v[156:159], off sc1
	v_pk_mul_f32 v[160:161], v[120:121], v[146:147] op_sel_hi:[1,0]
	s_nop 0
	v_pk_mul_f32 v[158:159], v[116:117], v[146:147] op_sel_hi:[1,0]
	v_pk_mul_f32 v[156:157], v[114:115], v[146:147] op_sel_hi:[1,0]
	s_nop 0
	v_cvt_pk_bf16_f32 v156, v156, v157
	v_cvt_pk_bf16_f32 v157, v158, v159
	v_pk_mul_f32 v[158:159], v[118:119], v[146:147] op_sel_hi:[1,0]
	s_nop 0
	v_cvt_pk_bf16_f32 v158, v158, v159
	v_cvt_pk_bf16_f32 v159, v160, v161
	global_store_dwordx4 v[150:151], v[156:159], off offset:256 sc1
	v_mov_b32_e32 v150, v147
	v_pk_mul_f32 v[146:147], v[24:25], v[150:151] op_sel_hi:[1,0]
	v_pk_mul_f32 v[156:157], v[22:23], v[150:151] op_sel_hi:[1,0]
	v_pk_mul_f32 v[158:159], v[18:19], v[150:151] op_sel_hi:[1,0]
	v_cvt_pk_bf16_f32 v156, v156, v157
	v_cvt_pk_bf16_f32 v157, v146, v147
	v_pk_mul_f32 v[146:147], v[20:21], v[150:151] op_sel_hi:[1,0]
	v_lshl_add_u64 v[160:161], v[148:149], 0, s[58:59]
	s_mov_b32 s58, 0xb0000
	v_cvt_pk_bf16_f32 v158, v158, v159
	v_cvt_pk_bf16_f32 v159, v146, v147
	v_add_co_u32_e32 v146, vcc, s58, v148
	s_nop 1
	v_addc_co_u32_e32 v147, vcc, 0, v149, vcc
	global_store_dwordx4 v[146:147], v[156:159], off sc1
	v_pk_mul_f32 v[148:149], v[124:125], v[150:151] op_sel_hi:[1,0]
	v_pk_mul_f32 v[146:147], v[122:123], v[150:151] op_sel_hi:[1,0]
	v_pk_mul_f32 v[156:157], v[128:129], v[150:151] op_sel_hi:[1,0]
	v_cvt_pk_bf16_f32 v146, v146, v147
	v_cvt_pk_bf16_f32 v147, v148, v149
	v_pk_mul_f32 v[148:149], v[126:127], v[150:151] op_sel_hi:[1,0]
	s_andn2_b64 vcc, exec, s[6:7]
	v_cvt_pk_bf16_f32 v148, v148, v149
	v_cvt_pk_bf16_f32 v149, v156, v157
	global_store_dwordx4 v[160:161], v[146:149], off offset:256 sc1
.Lmy_wtj_p1:
	s_cbranch_vccnz .LBB0_204
	s_andn2_b64 vcc, exec, s[8:9]
	s_cbranch_vccnz .LBB0_190
	s_barrier
	s_branch .LBB0_190
